# e51 + pool-weight-fold workgroups wait only for the raw/pool_w counter (fold GEMM) and the GEMV counter (rmsnorm rows), never the full P0->P1 barrier
# baseline (speedup 1.0000x reference)
; __global__ void __launch_bounds__(NTHREADS, 2) mk_fwd(Args a) {
;     ...
;                    if (b2 < 16) transpose_dispatch(b2 * 8 + wave, a.in[7], a.in[20], a.in[18], a.in[8], a.ws, scr, lane);
;                    for (int it = 80 + 3 * b2; it < 80 + 3 * b2 + 3; ++it) transpose_dispatch(it * 8 + wave, a.in[7], a.in[20], a.in[18], a.in[8], a.ws, scr, lane);
;                    if (b2 >= 16) transpose_dispatch((272 + b2 - 16) * 8 + wave, a.in[7], a.in[20], a.in[18], a.in[8], a.ws, scr, lane); } );
.LBB0_52:
	s_waitcnt vmcnt(0)
	s_barrier
	s_mov_b64 s[98:99], exec
	s_and_b64 exec, exec, s[82:83]
	s_cbranch_execz .Lp0_cnt
	v_mov_b32_e32 v252, 0xe040
	v_mov_b32_e32 v253, 1
	global_atomic_add v252, v253, s[50:51]

; #define SUB(i, ...) do { if (PROBE_PH == phk && PROBE_SUB == (i)) { __syncthreads(); tp0 = __builtin_amdgcn_s_memrealtime(); } __VA_ARGS__ if (PROBE_PH == phk && PROBE_SUB == (i)) { asm volatile("s_waitcnt vmcnt(0)" ::: "memory"); __syncthreads(); tp1 = __builtin_amdgcn_s_memrealtime(); } } while (0)
; __global__ void __launch_bounds__(NTHREADS, 2) mk_fwd(Args a) {
;     ...
;         { pg8::ListOrder S; S.init(32, 1, 8, G, vcu >= 128 && vcu < 160 ? vcu - 128 : 1 << 20);
;           EpiWp E{(f16*)(a.ws + WS_WIN)};
;           SUB(3, pg8::gemm_phase<CfgWp, EpiWp, pg8::ListOrder, true, true>(lds, (const char*)(a.ws + WS_WPOOL), (const char*)(a.ws + WS_WRAW), S, E); ); }
.LBB0_165:
	s_and_saveexec_b64 s[2:3], s[82:83]
	s_cbranch_execz .Lp1_waited
	s_and_b32 s98, s81, 0xffffffe0
	s_cmpk_eq_i32 s98, 0x80
	s_mov_b32 s98, 0xe000
	s_movk_i32 s101, 0xc0
	s_cbranch_scc0 .Lp1_wsel
	s_mov_b32 s98, 0xe040
	s_movk_i32 s101, 64

; #define SUB(i, ...) do { if (PROBE_PH == phk && PROBE_SUB == (i)) { __syncthreads(); tp0 = __builtin_amdgcn_s_memrealtime(); } __VA_ARGS__ if (PROBE_PH == phk && PROBE_SUB == (i)) { asm volatile("s_waitcnt vmcnt(0)" ::: "memory"); __syncthreads(); tp1 = __builtin_amdgcn_s_memrealtime(); } } while (0)
; __global__ void __launch_bounds__(NTHREADS, 2) mk_fwd(Args a) {
;     ...
;           SUB(3, pg8::gemm_phase<CfgWp, EpiWp, pg8::ListOrder, true, true>(lds, (const char*)(a.ws + WS_WPOOL), (const char*)(a.ws + WS_WRAW), S, E); ); }
;         SUB(1, norm_rows(vcu * NWAVES + wave, lane, a.in[0], a.in[2], a.in[6], (const float*)(a.ws + WS_MOD), (f16*)(a.ws + WS_H)); );
.LBB0_178:
	s_waitcnt vmcnt(0)
	v_readlane_b32 s76, v254, 36
	v_readlane_b32 s18, v254, 34
	s_mov_b32 s81, s52
	s_mov_b64 s[78:79], s[56:57]
	s_mov_b32 s52, s64
	s_mov_b64 s[82:83], s[66:67]
	v_readlane_b32 s77, v254, 37
	v_readlane_b32 s19, v254, 35
	s_mov_b32 s20, s65
	s_barrier
	s_and_b32 vcc_lo, s81, 0xffffffe0
	s_cmpk_eq_i32 vcc_lo, 0x80
	s_cbranch_scc0 .Lp1_w2_skip
	s_and_saveexec_b64 s[2:3], s[82:83]
	s_cbranch_execz .Lp1_w2_done
	v_mov_b32_e32 v2, 0xe000
	s_mov_b32 s101, 0
.Lp1_w2:
	global_load_dword v3, v2, s[50:51] sc1
	s_add_u32 s101, s101, 1
	s_waitcnt vmcnt(0)
	v_readfirstlane_b32 vcc_lo, v3
	s_cmp_ge_u32 vcc_lo, 0xc0
	s_cbranch_scc1 .Lp1_w2_polled
	s_cmp_gt_u32 s101, 0x4000
	s_cbranch_scc1 .Lp1_w2_polled
	s_sleep 1
	s_branch .Lp1_w2
